# adds: relu^2 (up-projection) epilogue rewritten by hand: in-place max/pk_mul/cvt per 8 columns, stores via scalar Z base + 32-bit lane offset (285 instead of ~630 instructions per unit)
# baseline (speedup 1.0000x reference)
.LBB0_810:
	v_lshl_add_u32 v147, s40, 8, v1
	v_lshl_or_b32 v146, s63, 8, v149
	v_lshlrev_b32_e32 v147, 15, v147
	v_lshl_add_u32 v146, v146, 1, v147
	v_max_f32_e32 v126, 0, v126
	v_max_f32_e32 v127, 0, v127
	v_max_f32_e32 v128, 0, v128
	v_max_f32_e32 v129, 0, v129
	v_max_f32_e32 v122, 0, v122
	v_max_f32_e32 v123, 0, v123
	v_max_f32_e32 v124, 0, v124
	v_max_f32_e32 v125, 0, v125
	v_pk_mul_f32 v[126:127], v[126:127], v[126:127]
	v_pk_mul_f32 v[128:129], v[128:129], v[128:129]
	v_pk_mul_f32 v[122:123], v[122:123], v[122:123]
	v_pk_mul_f32 v[124:125], v[124:125], v[124:125]
	v_cvt_pk_bf16_f32 v126, v126, v127
	v_cvt_pk_bf16_f32 v127, v128, v129
	v_cvt_pk_bf16_f32 v128, v122, v123
	v_cvt_pk_bf16_f32 v129, v124, v125
	global_store_dwordx4 v146, v[126:129], s[86:87]
	v_max_f32_e32 v118, 0, v118
	v_max_f32_e32 v119, 0, v119
	v_max_f32_e32 v120, 0, v120
	v_max_f32_e32 v121, 0, v121
	v_max_f32_e32 v114, 0, v114
	v_max_f32_e32 v115, 0, v115
	v_max_f32_e32 v116, 0, v116
	v_max_f32_e32 v117, 0, v117
	v_pk_mul_f32 v[118:119], v[118:119], v[118:119]
	v_pk_mul_f32 v[120:121], v[120:121], v[120:121]
	v_pk_mul_f32 v[114:115], v[114:115], v[114:115]
	v_pk_mul_f32 v[116:117], v[116:117], v[116:117]
	v_cvt_pk_bf16_f32 v118, v118, v119
	v_cvt_pk_bf16_f32 v119, v120, v121
	v_cvt_pk_bf16_f32 v120, v114, v115
	v_cvt_pk_bf16_f32 v121, v116, v117
	global_store_dwordx4 v146, v[118:121], s[86:87] offset:256
	v_add_u32_e32 v147, 0x80000, v146
	v_max_f32_e32 v110, 0, v110
	v_max_f32_e32 v111, 0, v111
	v_max_f32_e32 v112, 0, v112
	v_max_f32_e32 v113, 0, v113
	v_max_f32_e32 v106, 0, v106
	v_max_f32_e32 v107, 0, v107
	v_max_f32_e32 v108, 0, v108
	v_max_f32_e32 v109, 0, v109
	v_pk_mul_f32 v[110:111], v[110:111], v[110:111]
	v_pk_mul_f32 v[112:113], v[112:113], v[112:113]
	v_pk_mul_f32 v[106:107], v[106:107], v[106:107]
	v_pk_mul_f32 v[108:109], v[108:109], v[108:109]
	v_cvt_pk_bf16_f32 v110, v110, v111
	v_cvt_pk_bf16_f32 v111, v112, v113
	v_cvt_pk_bf16_f32 v112, v106, v107
	v_cvt_pk_bf16_f32 v113, v108, v109
	global_store_dwordx4 v147, v[110:113], s[86:87]
	v_max_f32_e32 v102, 0, v102
	v_max_f32_e32 v103, 0, v103
	v_max_f32_e32 v104, 0, v104
	v_max_f32_e32 v105, 0, v105
	v_max_f32_e32 v98, 0, v98
	v_max_f32_e32 v99, 0, v99
	v_max_f32_e32 v100, 0, v100
	v_max_f32_e32 v101, 0, v101
	v_pk_mul_f32 v[102:103], v[102:103], v[102:103]
	v_pk_mul_f32 v[104:105], v[104:105], v[104:105]
	v_pk_mul_f32 v[98:99], v[98:99], v[98:99]
	v_pk_mul_f32 v[100:101], v[100:101], v[100:101]
	v_cvt_pk_bf16_f32 v102, v102, v103
	v_cvt_pk_bf16_f32 v103, v104, v105
	v_cvt_pk_bf16_f32 v104, v98, v99
	v_cvt_pk_bf16_f32 v105, v100, v101
	global_store_dwordx4 v147, v[102:105], s[86:87] offset:256
	v_add_u32_e32 v147, 0x100000, v146
	v_max_f32_e32 v94, 0, v94
	v_max_f32_e32 v95, 0, v95
	v_max_f32_e32 v96, 0, v96
	v_max_f32_e32 v97, 0, v97
	v_max_f32_e32 v90, 0, v90
	v_max_f32_e32 v91, 0, v91
	v_max_f32_e32 v92, 0, v92
	v_max_f32_e32 v93, 0, v93
	v_pk_mul_f32 v[94:95], v[94:95], v[94:95]
	v_pk_mul_f32 v[96:97], v[96:97], v[96:97]
	v_pk_mul_f32 v[90:91], v[90:91], v[90:91]
	v_pk_mul_f32 v[92:93], v[92:93], v[92:93]
	v_cvt_pk_bf16_f32 v94, v94, v95
	v_cvt_pk_bf16_f32 v95, v96, v97
	v_cvt_pk_bf16_f32 v96, v90, v91
	v_cvt_pk_bf16_f32 v97, v92, v93
	global_store_dwordx4 v147, v[94:97], s[86:87]
	v_max_f32_e32 v86, 0, v86
	v_max_f32_e32 v87, 0, v87
	v_max_f32_e32 v88, 0, v88
	v_max_f32_e32 v89, 0, v89
	v_max_f32_e32 v82, 0, v82
	v_max_f32_e32 v83, 0, v83
	v_max_f32_e32 v84, 0, v84
	v_max_f32_e32 v85, 0, v85
	v_pk_mul_f32 v[86:87], v[86:87], v[86:87]
	v_pk_mul_f32 v[88:89], v[88:89], v[88:89]
	v_pk_mul_f32 v[82:83], v[82:83], v[82:83]
	v_pk_mul_f32 v[84:85], v[84:85], v[84:85]
	v_cvt_pk_bf16_f32 v86, v86, v87
	v_cvt_pk_bf16_f32 v87, v88, v89
	v_cvt_pk_bf16_f32 v88, v82, v83
	v_cvt_pk_bf16_f32 v89, v84, v85
	global_store_dwordx4 v147, v[86:89], s[86:87] offset:256
	v_add_u32_e32 v147, 0x180000, v146
	v_max_f32_e32 v78, 0, v78
	v_max_f32_e32 v79, 0, v79
	v_max_f32_e32 v80, 0, v80
	v_max_f32_e32 v81, 0, v81
	v_max_f32_e32 v74, 0, v74
	v_max_f32_e32 v75, 0, v75
	v_max_f32_e32 v76, 0, v76
	v_max_f32_e32 v77, 0, v77
	v_pk_mul_f32 v[78:79], v[78:79], v[78:79]
	v_pk_mul_f32 v[80:81], v[80:81], v[80:81]
	v_pk_mul_f32 v[74:75], v[74:75], v[74:75]
	v_pk_mul_f32 v[76:77], v[76:77], v[76:77]
	v_cvt_pk_bf16_f32 v78, v78, v79
	v_cvt_pk_bf16_f32 v79, v80, v81
	v_cvt_pk_bf16_f32 v80, v74, v75
	v_cvt_pk_bf16_f32 v81, v76, v77
	global_store_dwordx4 v147, v[78:81], s[86:87]
	v_max_f32_e32 v70, 0, v70
	v_max_f32_e32 v71, 0, v71
	v_max_f32_e32 v72, 0, v72
	v_max_f32_e32 v73, 0, v73
	v_max_f32_e32 v66, 0, v66
	v_max_f32_e32 v67, 0, v67
	v_max_f32_e32 v68, 0, v68
	v_max_f32_e32 v69, 0, v69
	v_pk_mul_f32 v[70:71], v[70:71], v[70:71]
	v_pk_mul_f32 v[72:73], v[72:73], v[72:73]
	v_pk_mul_f32 v[66:67], v[66:67], v[66:67]
	v_pk_mul_f32 v[68:69], v[68:69], v[68:69]
	v_cvt_pk_bf16_f32 v70, v70, v71
	v_cvt_pk_bf16_f32 v71, v72, v73
	v_cvt_pk_bf16_f32 v72, v66, v67
	v_cvt_pk_bf16_f32 v73, v68, v69
	global_store_dwordx4 v147, v[70:73], s[86:87] offset:256
	v_add_u32_e32 v147, 0x400000, v146
	v_max_f32_e32 v62, 0, v62
	v_max_f32_e32 v63, 0, v63
	v_max_f32_e32 v64, 0, v64
	v_max_f32_e32 v65, 0, v65
	v_max_f32_e32 v58, 0, v58
	v_max_f32_e32 v59, 0, v59
	v_max_f32_e32 v60, 0, v60
	v_max_f32_e32 v61, 0, v61
	v_pk_mul_f32 v[62:63], v[62:63], v[62:63]
	v_pk_mul_f32 v[64:65], v[64:65], v[64:65]
	v_pk_mul_f32 v[58:59], v[58:59], v[58:59]
	v_pk_mul_f32 v[60:61], v[60:61], v[60:61]
	v_cvt_pk_bf16_f32 v62, v62, v63
	v_cvt_pk_bf16_f32 v63, v64, v65
	v_cvt_pk_bf16_f32 v64, v58, v59
	v_cvt_pk_bf16_f32 v65, v60, v61
	global_store_dwordx4 v147, v[62:65], s[86:87]
	v_max_f32_e32 v54, 0, v54
	v_max_f32_e32 v55, 0, v55
	v_max_f32_e32 v56, 0, v56
	v_max_f32_e32 v57, 0, v57
	v_max_f32_e32 v50, 0, v50
	v_max_f32_e32 v51, 0, v51
	v_max_f32_e32 v52, 0, v52
	v_max_f32_e32 v53, 0, v53
	v_pk_mul_f32 v[54:55], v[54:55], v[54:55]
	v_pk_mul_f32 v[56:57], v[56:57], v[56:57]
	v_pk_mul_f32 v[50:51], v[50:51], v[50:51]
	v_pk_mul_f32 v[52:53], v[52:53], v[52:53]
	v_cvt_pk_bf16_f32 v54, v54, v55
	v_cvt_pk_bf16_f32 v55, v56, v57
	v_cvt_pk_bf16_f32 v56, v50, v51
	v_cvt_pk_bf16_f32 v57, v52, v53
	global_store_dwordx4 v147, v[54:57], s[86:87] offset:256
	v_add_u32_e32 v147, 0x480000, v146
	v_max_f32_e32 v46, 0, v46
	v_max_f32_e32 v47, 0, v47
	v_max_f32_e32 v48, 0, v48
	v_max_f32_e32 v49, 0, v49
	v_max_f32_e32 v42, 0, v42
	v_max_f32_e32 v43, 0, v43
	v_max_f32_e32 v44, 0, v44
	v_max_f32_e32 v45, 0, v45
	v_pk_mul_f32 v[46:47], v[46:47], v[46:47]
	v_pk_mul_f32 v[48:49], v[48:49], v[48:49]
	v_pk_mul_f32 v[42:43], v[42:43], v[42:43]
	v_pk_mul_f32 v[44:45], v[44:45], v[44:45]
	v_cvt_pk_bf16_f32 v46, v46, v47
	v_cvt_pk_bf16_f32 v47, v48, v49
	v_cvt_pk_bf16_f32 v48, v42, v43
	v_cvt_pk_bf16_f32 v49, v44, v45
	global_store_dwordx4 v147, v[46:49], s[86:87]
	v_max_f32_e32 v38, 0, v38
	v_max_f32_e32 v39, 0, v39
	v_max_f32_e32 v40, 0, v40
	v_max_f32_e32 v41, 0, v41
	v_max_f32_e32 v34, 0, v34
	v_max_f32_e32 v35, 0, v35
	v_max_f32_e32 v36, 0, v36
	v_max_f32_e32 v37, 0, v37
	v_pk_mul_f32 v[38:39], v[38:39], v[38:39]
	v_pk_mul_f32 v[40:41], v[40:41], v[40:41]
	v_pk_mul_f32 v[34:35], v[34:35], v[34:35]
	v_pk_mul_f32 v[36:37], v[36:37], v[36:37]
	v_cvt_pk_bf16_f32 v38, v38, v39
	v_cvt_pk_bf16_f32 v39, v40, v41
	v_cvt_pk_bf16_f32 v40, v34, v35
	v_cvt_pk_bf16_f32 v41, v36, v37
	global_store_dwordx4 v147, v[38:41], s[86:87] offset:256
	v_add_u32_e32 v147, 0x500000, v146
	v_max_f32_e32 v30, 0, v30
	v_max_f32_e32 v31, 0, v31
	v_max_f32_e32 v32, 0, v32
	v_max_f32_e32 v33, 0, v33
	v_max_f32_e32 v26, 0, v26
	v_max_f32_e32 v27, 0, v27
	v_max_f32_e32 v28, 0, v28
	v_max_f32_e32 v29, 0, v29
	v_pk_mul_f32 v[30:31], v[30:31], v[30:31]
	v_pk_mul_f32 v[32:33], v[32:33], v[32:33]
	v_pk_mul_f32 v[26:27], v[26:27], v[26:27]
	v_pk_mul_f32 v[28:29], v[28:29], v[28:29]
	v_cvt_pk_bf16_f32 v30, v30, v31
	v_cvt_pk_bf16_f32 v31, v32, v33
	v_cvt_pk_bf16_f32 v32, v26, v27
	v_cvt_pk_bf16_f32 v33, v28, v29
	global_store_dwordx4 v147, v[30:33], s[86:87]
	v_max_f32_e32 v22, 0, v22
	v_max_f32_e32 v23, 0, v23
	v_max_f32_e32 v24, 0, v24
	v_max_f32_e32 v25, 0, v25
	v_max_f32_e32 v18, 0, v18
	v_max_f32_e32 v19, 0, v19
	v_max_f32_e32 v20, 0, v20
	v_max_f32_e32 v21, 0, v21
	v_pk_mul_f32 v[22:23], v[22:23], v[22:23]
	v_pk_mul_f32 v[24:25], v[24:25], v[24:25]
	v_pk_mul_f32 v[18:19], v[18:19], v[18:19]
	v_pk_mul_f32 v[20:21], v[20:21], v[20:21]
	v_cvt_pk_bf16_f32 v22, v22, v23
	v_cvt_pk_bf16_f32 v23, v24, v25
	v_cvt_pk_bf16_f32 v24, v18, v19
	v_cvt_pk_bf16_f32 v25, v20, v21
	global_store_dwordx4 v147, v[22:25], s[86:87] offset:256
	v_add_u32_e32 v147, 0x580000, v146
	v_max_f32_e32 v14, 0, v14
	v_max_f32_e32 v15, 0, v15
	v_max_f32_e32 v16, 0, v16
	v_max_f32_e32 v17, 0, v17
	v_max_f32_e32 v10, 0, v10
	v_max_f32_e32 v11, 0, v11
	v_max_f32_e32 v12, 0, v12
	v_max_f32_e32 v13, 0, v13
	v_pk_mul_f32 v[14:15], v[14:15], v[14:15]
	v_pk_mul_f32 v[16:17], v[16:17], v[16:17]
	v_pk_mul_f32 v[10:11], v[10:11], v[10:11]
	v_pk_mul_f32 v[12:13], v[12:13], v[12:13]
	v_cvt_pk_bf16_f32 v14, v14, v15
	v_cvt_pk_bf16_f32 v15, v16, v17
	v_cvt_pk_bf16_f32 v16, v10, v11
	v_cvt_pk_bf16_f32 v17, v12, v13
	global_store_dwordx4 v147, v[14:17], s[86:87]
	v_max_f32_e32 v6, 0, v6
	v_max_f32_e32 v7, 0, v7
	v_max_f32_e32 v8, 0, v8
	v_max_f32_e32 v9, 0, v9
	v_max_f32_e32 v2, 0, v2
	v_max_f32_e32 v3, 0, v3
	v_max_f32_e32 v4, 0, v4
	v_max_f32_e32 v5, 0, v5
	v_pk_mul_f32 v[6:7], v[6:7], v[6:7]
	v_pk_mul_f32 v[8:9], v[8:9], v[8:9]
	v_pk_mul_f32 v[2:3], v[2:3], v[2:3]
	v_pk_mul_f32 v[4:5], v[4:5], v[4:5]
	v_cvt_pk_bf16_f32 v6, v6, v7
	v_cvt_pk_bf16_f32 v7, v8, v9
	v_cvt_pk_bf16_f32 v8, v2, v3
	v_cvt_pk_bf16_f32 v9, v4, v5
	global_store_dwordx4 v147, v[6:9], s[86:87] offset:256
	s_andn2_b64 vcc, exec, s[0:1]
	s_mov_b64 s[0:1], -1
	s_cbranch_vccnz .LBB0_803
	s_andn2_b64 vcc, exec, s[4:5]
	s_cbranch_vccnz .LBB0_802
	s_barrier
	s_branch .LBB0_802
